# grid barrier: the invalidate is issued right behind the arrival atomic (vmcnt(1) for the returned count), ahead of the leader's write-back
# speedup vs baseline: 1.0270x; 1.0046x over previous
.LBB0_331:
	s_waitcnt vmcnt(0)
	s_waitcnt lgkmcnt(0)
	s_barrier
	s_mov_b64 s[4:5], exec
	v_readlane_b32 s0, v126, 10
	v_readlane_b32 s1, v126, 11
	s_and_b64 s[0:1], s[4:5], s[0:1]
	s_mov_b64 exec, s[0:1]
	s_cbranch_execz .LBB0_383
	v_readlane_b32 s8, v126, 12
	v_readlane_b32 s9, v126, 13
	v_readlane_b32 s3, v126, 14
	v_mov_b32_e32 v0, 0
	v_mov_b32_e32 v1, 1
	s_lshl_b32 s3, s3, 8
	s_add_u32 s0, s8, s3
	s_addc_u32 s1, s9, 0
	s_add_u32 s0, s0, 0x1400
	s_addc_u32 s1, s1, 0
	global_atomic_add v4, v0, v1, s[0:1] sc0
	buffer_inv sc1
	v_mov_b32_e32 v5, 0x23ff0
	ds_read2_b32 v[2:3], v5 offset1:1
	s_add_u32 s8, s8, 0x3400
	s_addc_u32 s9, s9, 0
	s_sub_i32 s3, 3, s90
	s_mov_b32 s7, 0
	s_waitcnt lgkmcnt(0)
	v_readfirstlane_b32 s1, v2
	v_readfirstlane_b32 s6, v3
	s_mul_i32 s1, s1, s3
	s_mul_i32 s6, s6, s3
	s_waitcnt vmcnt(1)
	v_readfirstlane_b32 s0, v4
	s_add_i32 s0, s0, 1
	s_cmp_lg_u32 s0, s1
	s_cbranch_scc1 .Lgb2_poll
	buffer_wbl2 sc1
	s_waitcnt vmcnt(0)
	global_atomic_add v0, v1, s[8:9]

.LBB0_535:
	s_cmp_lt_i32 s91, 5
	s_cbranch_scc1 .LBB0_589
	s_waitcnt vmcnt(0)
	s_waitcnt lgkmcnt(0)
	s_barrier
	s_mov_b64 s[4:5], exec
	v_readlane_b32 s0, v126, 10
	v_readlane_b32 s1, v126, 11
	s_and_b64 s[0:1], s[4:5], s[0:1]
	s_mov_b64 exec, s[0:1]
	s_cbranch_execz .LBB0_588
	v_readlane_b32 s8, v126, 12
	v_readlane_b32 s9, v126, 13
	v_readlane_b32 s3, v126, 14
	v_mov_b32_e32 v0, 0
	v_mov_b32_e32 v1, 1
	s_lshl_b32 s3, s3, 8
	s_add_u32 s0, s8, s3
	s_addc_u32 s1, s9, 0
	s_add_u32 s0, s0, 0x1400
	s_addc_u32 s1, s1, 0
	global_atomic_add v4, v0, v1, s[0:1] sc0
	buffer_inv sc1
	v_mov_b32_e32 v5, 0x23ff0
	ds_read2_b32 v[2:3], v5 offset1:1
	s_add_u32 s8, s8, 0x3400
	s_addc_u32 s9, s9, 0
	s_sub_i32 s3, 4, s90
	s_mov_b32 s7, 0
	s_waitcnt lgkmcnt(0)
	v_readfirstlane_b32 s1, v2
	v_readfirstlane_b32 s6, v3
	s_mul_i32 s1, s1, s3
	s_mul_i32 s6, s6, s3
	s_waitcnt vmcnt(1)
	v_readfirstlane_b32 s0, v4
	s_add_i32 s0, s0, 1
	s_cmp_lg_u32 s0, s1
	s_cbranch_scc1 .Lgb3_poll
	buffer_wbl2 sc1
	s_waitcnt vmcnt(0)
	global_atomic_add v0, v1, s[8:9]

.LBB0_611:
	s_cmp_lt_i32 s91, 6
	s_cbranch_scc1 .LBB0_665
	s_waitcnt vmcnt(0)
	s_waitcnt lgkmcnt(0)
	s_barrier
	s_mov_b64 s[6:7], exec
	v_readlane_b32 s0, v126, 10
	v_readlane_b32 s1, v126, 11
	s_and_b64 s[0:1], s[6:7], s[0:1]
	s_mov_b64 exec, s[0:1]
	s_cbranch_execz .LBB0_664
	v_readlane_b32 s8, v126, 12
	v_readlane_b32 s9, v126, 13
	v_readlane_b32 s3, v126, 14
	v_mov_b32_e32 v0, 0
	v_mov_b32_e32 v1, 1
	s_lshl_b32 s3, s3, 8
	s_add_u32 s0, s8, s3
	s_addc_u32 s1, s9, 0
	s_add_u32 s0, s0, 0x1400
	s_addc_u32 s1, s1, 0
	global_atomic_add v4, v0, v1, s[0:1] sc0
	buffer_inv sc1
	v_mov_b32_e32 v5, 0x23ff0
	ds_read2_b32 v[2:3], v5 offset1:1
	s_add_u32 s8, s8, 0x3400
	s_addc_u32 s9, s9, 0
	s_sub_i32 s3, 5, s90
	s_mov_b32 s5, 0
	s_waitcnt lgkmcnt(0)
	v_readfirstlane_b32 s1, v2
	v_readfirstlane_b32 s4, v3
	s_mul_i32 s1, s1, s3
	s_mul_i32 s4, s4, s3
	s_waitcnt vmcnt(1)
	v_readfirstlane_b32 s0, v4
	s_add_i32 s0, s0, 1
	s_cmp_lg_u32 s0, s1
	s_cbranch_scc1 .Lgb4_poll
	buffer_wbl2 sc1
	s_waitcnt vmcnt(0)
	global_atomic_add v0, v1, s[8:9]

.LBB0_690:
	s_cmp_lt_i32 s91, 7
	s_cbranch_scc1 .LBB0_744
	s_waitcnt vmcnt(0)
	s_waitcnt lgkmcnt(0)
	s_barrier
	s_mov_b64 s[4:5], exec
	v_readlane_b32 s0, v126, 10
	v_readlane_b32 s1, v126, 11
	s_and_b64 s[0:1], s[4:5], s[0:1]
	s_mov_b64 exec, s[0:1]
	s_cbranch_execz .LBB0_743
	v_readlane_b32 s8, v126, 12
	v_readlane_b32 s9, v126, 13
	v_readlane_b32 s3, v126, 14
	v_mov_b32_e32 v0, 0
	v_mov_b32_e32 v1, 1
	s_lshl_b32 s3, s3, 8
	s_add_u32 s0, s8, s3
	s_addc_u32 s1, s9, 0
	s_add_u32 s0, s0, 0x1400
	s_addc_u32 s1, s1, 0
	global_atomic_add v4, v0, v1, s[0:1] sc0
	buffer_inv sc1
	v_mov_b32_e32 v5, 0x23ff0
	ds_read2_b32 v[2:3], v5 offset1:1
	s_add_u32 s8, s8, 0x3400
	s_addc_u32 s9, s9, 0
	s_sub_i32 s3, 6, s90
	s_mov_b32 s7, 0
	s_waitcnt lgkmcnt(0)
	v_readfirstlane_b32 s1, v2
	v_readfirstlane_b32 s6, v3
	s_mul_i32 s1, s1, s3
	s_mul_i32 s6, s6, s3
	s_waitcnt vmcnt(1)
	v_readfirstlane_b32 s0, v4
	s_add_i32 s0, s0, 1
	s_cmp_lg_u32 s0, s1
	s_cbranch_scc1 .Lgb5_poll
	buffer_wbl2 sc1
	s_waitcnt vmcnt(0)
	global_atomic_add v0, v1, s[8:9]

.LBB0_755:
	s_cmp_lt_i32 s91, 8
	s_cbranch_scc1 .LBB0_809
	s_waitcnt vmcnt(0)
	s_waitcnt lgkmcnt(0)
	s_barrier
	s_mov_b64 s[4:5], exec
	v_readlane_b32 s0, v126, 10
	v_readlane_b32 s1, v126, 11
	s_and_b64 s[0:1], s[4:5], s[0:1]
	s_mov_b64 exec, s[0:1]
	s_cbranch_execz .LBB0_808
	v_readlane_b32 s8, v126, 12
	v_readlane_b32 s9, v126, 13
	v_readlane_b32 s3, v126, 14
	v_mov_b32_e32 v0, 0
	v_mov_b32_e32 v1, 1
	s_lshl_b32 s3, s3, 8
	s_add_u32 s0, s8, s3
	s_addc_u32 s1, s9, 0
	s_add_u32 s0, s0, 0x1400
	s_addc_u32 s1, s1, 0
	global_atomic_add v4, v0, v1, s[0:1] sc0
	buffer_inv sc1
	v_mov_b32_e32 v5, 0x23ff0
	ds_read2_b32 v[2:3], v5 offset1:1
	s_add_u32 s8, s8, 0x3400
	s_addc_u32 s9, s9, 0
	s_sub_i32 s3, 7, s90
	s_mov_b32 s7, 0
	s_waitcnt lgkmcnt(0)
	v_readfirstlane_b32 s1, v2
	v_readfirstlane_b32 s6, v3
	s_mul_i32 s1, s1, s3
	s_mul_i32 s6, s6, s3
	s_waitcnt vmcnt(1)
	v_readfirstlane_b32 s0, v4
	s_add_i32 s0, s0, 1
	s_cmp_lg_u32 s0, s1
	s_cbranch_scc1 .Lgb6_poll
	buffer_wbl2 sc1
	s_waitcnt vmcnt(0)
	global_atomic_add v0, v1, s[8:9]

.LBB0_849:
	s_cmp_lt_i32 s91, 9
	s_cbranch_scc1 .LBB0_903
	s_waitcnt vmcnt(0)
	s_waitcnt lgkmcnt(0)
	s_barrier
	s_mov_b64 s[4:5], exec
	v_readlane_b32 s0, v126, 10
	v_readlane_b32 s1, v126, 11
	s_and_b64 s[0:1], s[4:5], s[0:1]
	s_mov_b64 exec, s[0:1]
	s_cbranch_execz .LBB0_902
	v_readlane_b32 s8, v126, 12
	v_readlane_b32 s9, v126, 13
	v_readlane_b32 s3, v126, 14
	v_mov_b32_e32 v0, 0
	v_mov_b32_e32 v1, 1
	s_lshl_b32 s3, s3, 8
	s_add_u32 s0, s8, s3
	s_addc_u32 s1, s9, 0
	s_add_u32 s0, s0, 0x1400
	s_addc_u32 s1, s1, 0
	global_atomic_add v4, v0, v1, s[0:1] sc0
	buffer_inv sc1
	v_mov_b32_e32 v5, 0x23ff0
	ds_read2_b32 v[2:3], v5 offset1:1
	s_add_u32 s8, s8, 0x3400
	s_addc_u32 s9, s9, 0
	s_sub_i32 s3, 8, s90
	s_mov_b32 s7, 0
	s_waitcnt lgkmcnt(0)
	v_readfirstlane_b32 s1, v2
	v_readfirstlane_b32 s6, v3
	s_mul_i32 s1, s1, s3
	s_mul_i32 s6, s6, s3
	s_waitcnt vmcnt(1)
	v_readfirstlane_b32 s0, v4
	s_add_i32 s0, s0, 1
	s_cmp_lg_u32 s0, s1
	s_cbranch_scc1 .Lgb7_poll
	buffer_wbl2 sc1
	s_waitcnt vmcnt(0)
	global_atomic_add v0, v1, s[8:9]

.LBB0_920:
	s_cmp_lt_i32 s91, 10
	s_cbranch_scc1 .LBB0_974
	s_waitcnt vmcnt(0)
	s_waitcnt vmcnt(0) lgkmcnt(0)
	s_barrier
	s_mov_b64 s[4:5], exec
	v_readlane_b32 s0, v126, 10
	v_readlane_b32 s1, v126, 11
	s_and_b64 s[0:1], s[4:5], s[0:1]
	s_mov_b64 exec, s[0:1]
	s_cbranch_execz .LBB0_973
	v_readlane_b32 s8, v126, 12
	v_readlane_b32 s9, v126, 13
	v_readlane_b32 s3, v126, 14
	v_mov_b32_e32 v0, 0
	v_mov_b32_e32 v1, 1
	s_lshl_b32 s3, s3, 8
	s_add_u32 s0, s8, s3
	s_addc_u32 s1, s9, 0
	s_add_u32 s0, s0, 0x1400
	s_addc_u32 s1, s1, 0
	global_atomic_add v4, v0, v1, s[0:1] sc0
	buffer_inv sc1
	v_mov_b32_e32 v5, 0x23ff0
	ds_read2_b32 v[2:3], v5 offset1:1
	s_add_u32 s8, s8, 0x3400
	s_addc_u32 s9, s9, 0
	s_sub_i32 s3, 9, s90
	s_mov_b32 s7, 0
	s_waitcnt lgkmcnt(0)
	v_readfirstlane_b32 s1, v2
	v_readfirstlane_b32 s6, v3
	s_mul_i32 s1, s1, s3
	s_mul_i32 s6, s6, s3
	s_waitcnt vmcnt(1)
	v_readfirstlane_b32 s0, v4
	s_add_i32 s0, s0, 1
	s_cmp_lg_u32 s0, s1
	s_cbranch_scc1 .Lgb8_poll
	buffer_wbl2 sc1
	s_waitcnt vmcnt(0)
	global_atomic_add v0, v1, s[8:9]

.LBB0_991:
	s_cmp_lt_i32 s91, 11
	s_cbranch_scc1 .LBB0_1045
	s_waitcnt vmcnt(0)
	s_waitcnt vmcnt(0) lgkmcnt(0)
	s_barrier
	s_mov_b64 s[4:5], exec
	v_readlane_b32 s0, v126, 10
	v_readlane_b32 s1, v126, 11
	s_and_b64 s[0:1], s[4:5], s[0:1]
	s_mov_b64 exec, s[0:1]
	s_cbranch_execz .LBB0_1044
	v_readlane_b32 s8, v126, 12
	v_readlane_b32 s9, v126, 13
	v_readlane_b32 s3, v126, 14
	v_mov_b32_e32 v0, 0
	v_mov_b32_e32 v1, 1
	s_lshl_b32 s3, s3, 8
	s_add_u32 s0, s8, s3
	s_addc_u32 s1, s9, 0
	s_add_u32 s0, s0, 0x1400
	s_addc_u32 s1, s1, 0
	global_atomic_add v4, v0, v1, s[0:1] sc0
	buffer_inv sc1
	v_mov_b32_e32 v5, 0x23ff0
	ds_read2_b32 v[2:3], v5 offset1:1
	s_add_u32 s8, s8, 0x3400
	s_addc_u32 s9, s9, 0
	s_sub_i32 s3, 10, s90
	s_mov_b32 s7, 0
	s_waitcnt lgkmcnt(0)
	v_readfirstlane_b32 s1, v2
	v_readfirstlane_b32 s6, v3
	s_mul_i32 s1, s1, s3
	s_mul_i32 s6, s6, s3
	s_waitcnt vmcnt(1)
	v_readfirstlane_b32 s0, v4
	s_add_i32 s0, s0, 1
	s_cmp_lg_u32 s0, s1
	s_cbranch_scc1 .Lgb9_poll
	buffer_wbl2 sc1
	s_waitcnt vmcnt(0)
	global_atomic_add v0, v1, s[8:9]

.LBB0_1055:
	s_or_b64 exec, exec, s[8:9]
	s_cmp_lt_i32 s91, 12
	s_cbranch_scc1 .LBB0_1109
	s_waitcnt vmcnt(0)
	s_waitcnt lgkmcnt(0)
	s_barrier
	s_mov_b64 s[4:5], exec
	v_readlane_b32 s0, v126, 10
	v_readlane_b32 s1, v126, 11
	s_and_b64 s[0:1], s[4:5], s[0:1]
	s_mov_b64 exec, s[0:1]
	s_cbranch_execz .LBB0_1108
	v_readlane_b32 s8, v126, 12
	v_readlane_b32 s9, v126, 13
	v_readlane_b32 s3, v126, 14
	v_mov_b32_e32 v0, 0
	v_mov_b32_e32 v1, 1
	s_lshl_b32 s3, s3, 8
	s_add_u32 s0, s8, s3
	s_addc_u32 s1, s9, 0
	s_add_u32 s0, s0, 0x1400
	s_addc_u32 s1, s1, 0
	global_atomic_add v4, v0, v1, s[0:1] sc0
	buffer_inv sc1
	v_mov_b32_e32 v5, 0x23ff0
	ds_read2_b32 v[2:3], v5 offset1:1
	s_add_u32 s8, s8, 0x3400
	s_addc_u32 s9, s9, 0
	s_sub_i32 s3, 11, s90
	s_mov_b32 s7, 0
	s_waitcnt lgkmcnt(0)
	v_readfirstlane_b32 s1, v2
	v_readfirstlane_b32 s6, v3
	s_mul_i32 s1, s1, s3
	s_mul_i32 s6, s6, s3
	s_waitcnt vmcnt(1)
	v_readfirstlane_b32 s0, v4
	s_add_i32 s0, s0, 1
	s_cmp_lg_u32 s0, s1
	s_cbranch_scc1 .Lgb10_poll
	buffer_wbl2 sc1
	s_waitcnt vmcnt(0)
	global_atomic_add v0, v1, s[8:9]

.LBB0_1153:
	s_waitcnt vmcnt(0)
	s_waitcnt vmcnt(0) lgkmcnt(0)
	s_barrier
	s_mov_b64 s[4:5], exec
	v_readlane_b32 s0, v126, 10
	v_readlane_b32 s1, v126, 11
	s_and_b64 s[0:1], s[4:5], s[0:1]
	s_mov_b64 exec, s[0:1]
	s_cbranch_execz .LBB0_1205
	v_readlane_b32 s8, v126, 12
	v_readlane_b32 s9, v126, 13
	v_readlane_b32 s3, v126, 14
	v_mov_b32_e32 v0, 0
	v_mov_b32_e32 v1, 1
	s_lshl_b32 s3, s3, 8
	s_add_u32 s0, s8, s3
	s_addc_u32 s1, s9, 0
	s_add_u32 s0, s0, 0x1400
	s_addc_u32 s1, s1, 0
	global_atomic_add v4, v0, v1, s[0:1] sc0
	buffer_inv sc1
	v_mov_b32_e32 v5, 0x23ff0
	ds_read2_b32 v[2:3], v5 offset1:1
	s_add_u32 s8, s8, 0x3400
	s_addc_u32 s9, s9, 0
	s_sub_i32 s3, 12, s90
	s_mov_b32 s7, 0
	s_waitcnt lgkmcnt(0)
	v_readfirstlane_b32 s1, v2
	v_readfirstlane_b32 s6, v3
	s_mul_i32 s1, s1, s3
	s_mul_i32 s6, s6, s3
	s_waitcnt vmcnt(1)
	v_readfirstlane_b32 s0, v4
	s_add_i32 s0, s0, 1
	s_cmp_lg_u32 s0, s1
	s_cbranch_scc1 .Lgb11_poll
	buffer_wbl2 sc1
	s_waitcnt vmcnt(0)
	global_atomic_add v0, v1, s[8:9]

.LBB0_1212:
	s_cmp_lt_i32 s91, 14
	s_cbranch_scc1 .LBB0_1266
	s_waitcnt vmcnt(0)
	s_waitcnt vmcnt(0) lgkmcnt(0)
	s_barrier
	s_mov_b64 s[6:7], exec
	v_readlane_b32 s0, v126, 10
	v_readlane_b32 s1, v126, 11
	s_and_b64 s[0:1], s[6:7], s[0:1]
	s_mov_b64 exec, s[0:1]
	s_cbranch_execz .LBB0_1265
	v_readlane_b32 s8, v126, 12
	v_readlane_b32 s9, v126, 13
	v_readlane_b32 s3, v126, 14
	v_mov_b32_e32 v0, 0
	v_mov_b32_e32 v1, 1
	s_lshl_b32 s3, s3, 8
	s_add_u32 s0, s8, s3
	s_addc_u32 s1, s9, 0
	s_add_u32 s0, s0, 0x1400
	s_addc_u32 s1, s1, 0
	global_atomic_add v4, v0, v1, s[0:1] sc0
	buffer_inv sc1
	v_mov_b32_e32 v5, 0x23ff0
	ds_read2_b32 v[2:3], v5 offset1:1
	s_add_u32 s8, s8, 0x3400
	s_addc_u32 s9, s9, 0
	s_sub_i32 s3, 13, s90
	s_mov_b32 s5, 0
	s_waitcnt lgkmcnt(0)
	v_readfirstlane_b32 s1, v2
	v_readfirstlane_b32 s4, v3
	s_mul_i32 s1, s1, s3
	s_mul_i32 s4, s4, s3
	s_waitcnt vmcnt(1)
	v_readfirstlane_b32 s0, v4
	s_add_i32 s0, s0, 1
	s_cmp_lg_u32 s0, s1
	s_cbranch_scc1 .Lgb12_poll
	buffer_wbl2 sc1
	s_waitcnt vmcnt(0)
	global_atomic_add v0, v1, s[8:9]

.LBB0_1291:
	s_cmp_lt_i32 s91, 15
	s_cbranch_scc1 .LBB0_1345
	s_waitcnt vmcnt(0)
	s_waitcnt vmcnt(0) lgkmcnt(0)
	s_barrier
	s_mov_b64 s[4:5], exec
	v_readlane_b32 s0, v126, 10
	v_readlane_b32 s1, v126, 11
	s_and_b64 s[0:1], s[4:5], s[0:1]
	s_mov_b64 exec, s[0:1]
	s_cbranch_execz .LBB0_1344
	v_readlane_b32 s8, v126, 12
	v_readlane_b32 s9, v126, 13
	v_readlane_b32 s3, v126, 14
	v_mov_b32_e32 v0, 0
	v_mov_b32_e32 v1, 1
	s_lshl_b32 s3, s3, 8
	s_add_u32 s0, s8, s3
	s_addc_u32 s1, s9, 0
	s_add_u32 s0, s0, 0x1400
	s_addc_u32 s1, s1, 0
	global_atomic_add v4, v0, v1, s[0:1] sc0
	buffer_inv sc1
	v_mov_b32_e32 v5, 0x23ff0
	ds_read2_b32 v[2:3], v5 offset1:1
	s_add_u32 s8, s8, 0x3400
	s_addc_u32 s9, s9, 0
	s_sub_i32 s3, 14, s90
	s_mov_b32 s7, 0
	s_waitcnt lgkmcnt(0)
	v_readfirstlane_b32 s1, v2
	v_readfirstlane_b32 s6, v3
	s_mul_i32 s1, s1, s3
	s_mul_i32 s6, s6, s3
	s_waitcnt vmcnt(1)
	v_readfirstlane_b32 s0, v4
	s_add_i32 s0, s0, 1
	s_cmp_lg_u32 s0, s1
	s_cbranch_scc1 .Lgb13_poll
	buffer_wbl2 sc1
	s_waitcnt vmcnt(0)
	global_atomic_add v0, v1, s[8:9]

.LBB0_1356:
	s_cmp_lt_i32 s91, 16
	s_cbranch_scc1 .LBB0_1410
	s_waitcnt vmcnt(0)
	s_waitcnt lgkmcnt(0)
	s_barrier
	s_mov_b64 s[4:5], exec
	v_readlane_b32 s0, v126, 10
	v_readlane_b32 s1, v126, 11
	s_and_b64 s[0:1], s[4:5], s[0:1]
	s_mov_b64 exec, s[0:1]
	s_cbranch_execz .LBB0_1409
	v_readlane_b32 s8, v126, 12
	v_readlane_b32 s9, v126, 13
	v_readlane_b32 s3, v126, 14
	v_mov_b32_e32 v0, 0
	v_mov_b32_e32 v1, 1
	s_lshl_b32 s3, s3, 8
	s_add_u32 s0, s8, s3
	s_addc_u32 s1, s9, 0
	s_add_u32 s0, s0, 0x1400
	s_addc_u32 s1, s1, 0
	global_atomic_add v4, v0, v1, s[0:1] sc0
	buffer_inv sc1
	v_mov_b32_e32 v5, 0x23ff0
	ds_read2_b32 v[2:3], v5 offset1:1
	s_add_u32 s8, s8, 0x3400
	s_addc_u32 s9, s9, 0
	s_sub_i32 s3, 15, s90
	s_mov_b32 s7, 0
	s_waitcnt lgkmcnt(0)
	v_readfirstlane_b32 s1, v2
	v_readfirstlane_b32 s6, v3
	s_mul_i32 s1, s1, s3
	s_mul_i32 s6, s6, s3
	s_waitcnt vmcnt(1)
	v_readfirstlane_b32 s0, v4
	s_add_i32 s0, s0, 1
	s_cmp_lg_u32 s0, s1
	s_cbranch_scc1 .Lgb14_poll
	buffer_wbl2 sc1
	s_waitcnt vmcnt(0)
	global_atomic_add v0, v1, s[8:9]

.LBB0_1450:
	s_cmp_lt_i32 s91, 17
	s_cbranch_scc1 .LBB0_1504
	s_waitcnt vmcnt(0)
	s_waitcnt vmcnt(0) lgkmcnt(0)
	s_barrier
	s_mov_b64 s[4:5], exec
	v_readlane_b32 s0, v126, 10
	v_readlane_b32 s1, v126, 11
	s_and_b64 s[0:1], s[4:5], s[0:1]
	s_mov_b64 exec, s[0:1]
	s_cbranch_execz .LBB0_1503
	v_readlane_b32 s8, v126, 12
	v_readlane_b32 s9, v126, 13
	v_readlane_b32 s3, v126, 14
	v_mov_b32_e32 v0, 0
	v_mov_b32_e32 v1, 1
	s_lshl_b32 s3, s3, 8
	s_add_u32 s0, s8, s3
	s_addc_u32 s1, s9, 0
	s_add_u32 s0, s0, 0x1400
	s_addc_u32 s1, s1, 0
	global_atomic_add v4, v0, v1, s[0:1] sc0
	buffer_inv sc1
	v_mov_b32_e32 v5, 0x23ff0
	ds_read2_b32 v[2:3], v5 offset1:1
	s_add_u32 s8, s8, 0x3400
	s_addc_u32 s9, s9, 0
	s_sub_i32 s3, 16, s90
	s_mov_b32 s7, 0
	s_waitcnt lgkmcnt(0)
	v_readfirstlane_b32 s1, v2
	v_readfirstlane_b32 s6, v3
	s_mul_i32 s1, s1, s3
	s_mul_i32 s6, s6, s3
	s_waitcnt vmcnt(1)
	v_readfirstlane_b32 s0, v4
	s_add_i32 s0, s0, 1
	s_cmp_lg_u32 s0, s1
	s_cbranch_scc1 .Lgb15_poll
	buffer_wbl2 sc1
	s_waitcnt vmcnt(0)
	global_atomic_add v0, v1, s[8:9]

.LBB0_1521:
	s_cmp_lt_i32 s91, 18
	s_cbranch_scc1 .LBB0_1575
	s_waitcnt vmcnt(0)
	s_waitcnt vmcnt(0) lgkmcnt(0)
	s_barrier
	s_mov_b64 s[4:5], exec
	v_readlane_b32 s0, v126, 10
	v_readlane_b32 s1, v126, 11
	s_and_b64 s[0:1], s[4:5], s[0:1]
	s_mov_b64 exec, s[0:1]
	s_cbranch_execz .LBB0_1574
	v_readlane_b32 s8, v126, 12
	v_readlane_b32 s9, v126, 13
	v_readlane_b32 s3, v126, 14
	v_mov_b32_e32 v0, 0
	v_mov_b32_e32 v1, 1
	s_lshl_b32 s3, s3, 8
	s_add_u32 s0, s8, s3
	s_addc_u32 s1, s9, 0
	s_add_u32 s0, s0, 0x1400
	s_addc_u32 s1, s1, 0
	global_atomic_add v4, v0, v1, s[0:1] sc0
	buffer_inv sc1
	v_mov_b32_e32 v5, 0x23ff0
	ds_read2_b32 v[2:3], v5 offset1:1
	s_add_u32 s8, s8, 0x3400
	s_addc_u32 s9, s9, 0
	s_sub_i32 s3, 17, s90
	s_mov_b32 s7, 0
	s_waitcnt lgkmcnt(0)
	v_readfirstlane_b32 s1, v2
	v_readfirstlane_b32 s6, v3
	s_mul_i32 s1, s1, s3
	s_mul_i32 s6, s6, s3
	s_waitcnt vmcnt(1)
	v_readfirstlane_b32 s0, v4
	s_add_i32 s0, s0, 1
	s_cmp_lg_u32 s0, s1
	s_cbranch_scc1 .Lgb16_poll
	buffer_wbl2 sc1
	s_waitcnt vmcnt(0)
	global_atomic_add v0, v1, s[8:9]

.LBB0_1592:
	s_cmp_lt_i32 s91, 19
	s_cbranch_scc1 .LBB0_1646
	s_waitcnt vmcnt(0)
	s_waitcnt vmcnt(0) lgkmcnt(0)
	s_barrier
	s_mov_b64 s[4:5], exec
	v_readlane_b32 s0, v126, 10
	v_readlane_b32 s1, v126, 11
	s_and_b64 s[0:1], s[4:5], s[0:1]
	s_mov_b64 exec, s[0:1]
	s_cbranch_execz .LBB0_1645
	v_readlane_b32 s8, v126, 12
	v_readlane_b32 s9, v126, 13
	v_readlane_b32 s3, v126, 14
	v_mov_b32_e32 v0, 0
	v_mov_b32_e32 v1, 1
	s_lshl_b32 s3, s3, 8
	s_add_u32 s0, s8, s3
	s_addc_u32 s1, s9, 0
	s_add_u32 s0, s0, 0x1400
	s_addc_u32 s1, s1, 0
	global_atomic_add v4, v0, v1, s[0:1] sc0
	buffer_inv sc1
	v_mov_b32_e32 v5, 0x23ff0
	ds_read2_b32 v[2:3], v5 offset1:1
	s_add_u32 s8, s8, 0x3400
	s_addc_u32 s9, s9, 0
	s_sub_i32 s3, 18, s90
	s_mov_b32 s7, 0
	s_waitcnt lgkmcnt(0)
	v_readfirstlane_b32 s1, v2
	v_readfirstlane_b32 s6, v3
	s_mul_i32 s1, s1, s3
	s_mul_i32 s6, s6, s3
	s_waitcnt vmcnt(1)
	v_readfirstlane_b32 s0, v4
	s_add_i32 s0, s0, 1
	s_cmp_lg_u32 s0, s1
	s_cbranch_scc1 .Lgb17_poll
	buffer_wbl2 sc1
	s_waitcnt vmcnt(0)
	global_atomic_add v0, v1, s[8:9]
